# mode-0 chunk scan: rank-1/rank-2 updates of both transition matrices moved to v_mfma_f32_4x4x1_16b_f32 (exact f32 fma), dots stay on VALU
# baseline (speedup 1.0000x reference)
; #define RW_LD_DOT(buf, hb) do { _Pragma("unroll") for (int q_ = 0; q_ < DB; ++q_) kd[buf][q_] = *(const LAS f32x4*)(st + 64 + 4 * (DB * (hb) + q_)); } while (0)
; template <int MODE> __device__ __forceinline__ void rwkv_item(const Params& P, int e, int c, int h, LAS float* slab, int lane) {
;     ...
;             for (int hb = 0; hb < NDB; ++hb) {
;                 if (NB == 2) { if (hb + 1 < NDB) RW_LD_DOT((hb + 1) & 1, hb + 1); else RW_LD_UPD(0, 0); } else RW_LD_DOT(0, hb);
;                 __builtin_amdgcn_sched_barrier(0);
; #pragma unroll
;                 for (int q = 0; q < DB; ++q) {
;                     const int qq = DB * hb + q; const f32x4 k4 = kd[hb & (NB - 1)][q];
;                     aS0 += S2[2 * qq] * (f32x2){k4.x, k4.y}; aS1 += S2[2 * qq + 1] * (f32x2){k4.z, k4.w};
;                     if (MODE == 0) { aC0 += C2[2 * qq] * (f32x2){k4.x, k4.y}; aC1 += C2[2 * qq + 1] * (f32x2){k4.z, k4.w}; }
;                 }
;                 __builtin_amdgcn_sched_barrier(0);
;             }
;             const float nsk = -((aS0.x + aS0.y) + (aS1.x + aS1.y));
;             const float nskC = -((aC0.x + aC0.y) + (aC1.x + aC1.y));
;             f32x2 y0 = {0.f, 0.f}, y1 = {0.f, 0.f};
; #pragma unroll
;             for (int qb = 0; qb < NUB; ++qb) {
;                 if (NB == 2) { if (qb + 1 < NUB) RW_LD_UPD((qb + 1) & 1, qb + 1); } else RW_LD_UPD(0, qb);
;                 __builtin_amdgcn_sched_barrier(0);
; #pragma unroll
;                 for (int q = 0; q < UB; ++q) {
;                     const int qq = UB * qb + q;
;                     const f32x4 w4 = wq[qb & (NB - 1)][q], b4 = bq[qb & (NB - 1)][q], k4 = kq[qb & (NB - 1)][q];
;                     if (MODE == 0) {
;                         S2[2 * qq] = S2[2 * qq] * (f32x2){w4.x, w4.y} + (f32x2){b4.x, b4.y} * nsk;
;                         S2[2 * qq + 1] = S2[2 * qq + 1] * (f32x2){w4.z, w4.w} + (f32x2){b4.z, b4.w} * nsk;
;                         C2[2 * qq] = C2[2 * qq] * (f32x2){w4.x, w4.y} + (f32x2){b4.x, b4.y} * nskC + (f32x2){k4.x, k4.y} * v;
;                         C2[2 * qq + 1] = C2[2 * qq + 1] * (f32x2){w4.z, w4.w} + (f32x2){b4.z, b4.w} * nskC + (f32x2){k4.z, k4.w} * v;
.Lm0_step:
	v_add_u32_e32 v152, 0x500, v129
	s_add_i32 s3, s21, s2
	v_add_u32_e32 v152, s2, v152
	v_and_b32_e32 v139, 3, v128
	v_mov_b32_e32 v233, s3
	v_lshl_add_u32 v139, v139, 2, s3
	ds_read_b32 v152, v152
	ds_read_b128 v[214:217], v233 offset:256
	ds_read_b128 v[234:237], v233 offset:272
	ds_read_b128 v[238:241], v233 offset:288
	ds_read_b128 v[242:245], v233 offset:304
	ds_read_b128 v[246:249], v233 offset:320
	ds_read_b128 v[140:143], v233 offset:336
	ds_read_b128 v[144:147], v233 offset:352
	ds_read_b128 v[148:151], v233 offset:368
	s_waitcnt lgkmcnt(7)
	v_pk_fma_f32 v[158:159], v[112:113], v[214:215], 0 op_sel_hi:[1,1,0]
	v_pk_fma_f32 v[160:161], v[114:115], v[216:217], 0 op_sel_hi:[1,1,0]
	v_pk_fma_f32 v[162:163], v[124:125], v[214:215], 0 op_sel_hi:[1,1,0]
	v_pk_fma_f32 v[164:165], v[126:127], v[216:217], 0 op_sel_hi:[1,1,0]
	ds_read_b128 v[214:217], v233 offset:384
	s_waitcnt lgkmcnt(7)
	v_pk_fma_f32 v[158:159], v[104:105], v[234:235], v[158:159]
	v_pk_fma_f32 v[160:161], v[106:107], v[236:237], v[160:161]
	v_pk_fma_f32 v[162:163], v[120:121], v[234:235], v[162:163]
	v_pk_fma_f32 v[164:165], v[122:123], v[236:237], v[164:165]
	ds_read_b128 v[234:237], v233 offset:400
	s_waitcnt lgkmcnt(7)
	v_pk_fma_f32 v[158:159], v[92:93], v[238:239], v[158:159]
	v_pk_fma_f32 v[160:161], v[94:95], v[240:241], v[160:161]
	v_pk_fma_f32 v[162:163], v[116:117], v[238:239], v[162:163]
	v_pk_fma_f32 v[164:165], v[118:119], v[240:241], v[164:165]
	ds_read_b128 v[238:241], v233 offset:416
	s_waitcnt lgkmcnt(7)
	v_pk_fma_f32 v[158:159], v[76:77], v[242:243], v[158:159]
	v_pk_fma_f32 v[160:161], v[78:79], v[244:245], v[160:161]
	v_pk_fma_f32 v[162:163], v[108:109], v[242:243], v[162:163]
	v_pk_fma_f32 v[164:165], v[110:111], v[244:245], v[164:165]
	ds_read_b128 v[242:245], v233 offset:432
	s_waitcnt lgkmcnt(7)
	v_pk_fma_f32 v[158:159], v[64:65], v[246:247], v[158:159]
	v_pk_fma_f32 v[160:161], v[66:67], v[248:249], v[160:161]
	v_pk_fma_f32 v[162:163], v[96:97], v[246:247], v[162:163]
	v_pk_fma_f32 v[164:165], v[98:99], v[248:249], v[164:165]
	ds_read_b128 v[246:249], v233 offset:448
	s_waitcnt lgkmcnt(7)
	v_pk_fma_f32 v[158:159], v[100:101], v[140:141], v[158:159]
	v_pk_fma_f32 v[160:161], v[102:103], v[142:143], v[160:161]
	v_pk_fma_f32 v[162:163], v[80:81], v[140:141], v[162:163]
	v_pk_fma_f32 v[164:165], v[82:83], v[142:143], v[164:165]
	ds_read_b128 v[140:143], v233 offset:464
	s_waitcnt lgkmcnt(7)
	v_pk_fma_f32 v[158:159], v[88:89], v[144:145], v[158:159]
	v_pk_fma_f32 v[160:161], v[90:91], v[146:147], v[160:161]
	v_pk_fma_f32 v[162:163], v[68:69], v[144:145], v[162:163]
	v_pk_fma_f32 v[164:165], v[70:71], v[146:147], v[164:165]
	ds_read_b128 v[144:147], v233 offset:480
	s_waitcnt lgkmcnt(7)
	v_pk_fma_f32 v[158:159], v[84:85], v[148:149], v[158:159]
	v_pk_fma_f32 v[160:161], v[86:87], v[150:151], v[160:161]
	v_pk_fma_f32 v[162:163], v[52:53], v[148:149], v[162:163]
	v_pk_fma_f32 v[164:165], v[54:55], v[150:151], v[164:165]
	ds_read_b128 v[148:151], v233 offset:496
	s_waitcnt lgkmcnt(7)
	v_pk_fma_f32 v[158:159], v[72:73], v[214:215], v[158:159]
	v_pk_fma_f32 v[160:161], v[74:75], v[216:217], v[160:161]
	v_pk_fma_f32 v[162:163], v[44:45], v[214:215], v[162:163]
	v_pk_fma_f32 v[164:165], v[46:47], v[216:217], v[164:165]
	ds_read_b32 v130, v139 offset:512
	s_waitcnt lgkmcnt(7)
	v_pk_fma_f32 v[158:159], v[60:61], v[234:235], v[158:159]
	v_pk_fma_f32 v[160:161], v[62:63], v[236:237], v[160:161]
	v_pk_fma_f32 v[162:163], v[32:33], v[234:235], v[162:163]
	v_pk_fma_f32 v[164:165], v[34:35], v[236:237], v[164:165]
	ds_read_b32 v131, v139 offset:528
	s_waitcnt lgkmcnt(7)
	v_pk_fma_f32 v[158:159], v[56:57], v[238:239], v[158:159]
	v_pk_fma_f32 v[160:161], v[58:59], v[240:241], v[160:161]
	v_pk_fma_f32 v[162:163], v[24:25], v[238:239], v[162:163]
	v_pk_fma_f32 v[164:165], v[26:27], v[240:241], v[164:165]
	ds_read_b32 v132, v139 offset:768
	s_waitcnt lgkmcnt(7)
	v_pk_fma_f32 v[158:159], v[48:49], v[242:243], v[158:159]
	v_pk_fma_f32 v[160:161], v[50:51], v[244:245], v[160:161]
	v_pk_fma_f32 v[162:163], v[16:17], v[242:243], v[162:163]
	v_pk_fma_f32 v[164:165], v[18:19], v[244:245], v[164:165]
	ds_read_b32 v133, v139 offset:544
	s_waitcnt lgkmcnt(7)
	v_pk_fma_f32 v[158:159], v[40:41], v[246:247], v[158:159]
	v_pk_fma_f32 v[160:161], v[42:43], v[248:249], v[160:161]
	v_pk_fma_f32 v[162:163], v[12:13], v[246:247], v[162:163]
	v_pk_fma_f32 v[164:165], v[14:15], v[248:249], v[164:165]
	ds_read_b32 v134, v139 offset:784
	s_waitcnt lgkmcnt(7)
	v_pk_fma_f32 v[158:159], v[36:37], v[140:141], v[158:159]
	v_pk_fma_f32 v[160:161], v[38:39], v[142:143], v[160:161]
	v_pk_fma_f32 v[162:163], v[8:9], v[140:141], v[162:163]
	v_pk_fma_f32 v[164:165], v[10:11], v[142:143], v[164:165]
	ds_read_b32 v135, v139 offset:560
	s_waitcnt lgkmcnt(7)
	v_pk_fma_f32 v[158:159], v[28:29], v[144:145], v[158:159]
	v_pk_fma_f32 v[160:161], v[30:31], v[146:147], v[160:161]
	v_pk_fma_f32 v[162:163], v[4:5], v[144:145], v[162:163]
	v_pk_fma_f32 v[164:165], v[6:7], v[146:147], v[164:165]
	ds_read_b32 v136, v139 offset:800
	s_waitcnt lgkmcnt(7)
	v_pk_fma_f32 v[158:159], v[20:21], v[148:149], v[158:159]
	v_pk_fma_f32 v[160:161], v[22:23], v[150:151], v[160:161]
	v_pk_fma_f32 v[162:163], v[0:1], v[148:149], v[162:163]
	v_pk_fma_f32 v[164:165], v[2:3], v[150:151], v[164:165]
	ds_read_b32 v138, v139 offset:576
	v_add_f32_e32 v208, v158, v159
	v_add_f32_e32 v209, v160, v161
	v_add_f32_e32 v250, v162, v163
	v_add_f32_e32 v251, v164, v165
	v_add_f32_e32 v208, v209, v208
	v_add_f32_e32 v250, v251, v250
	v_mul_f32_e32 v208, -1.0, v208
	v_mul_f32_e32 v250, -1.0, v250
	s_nop 1
	s_waitcnt lgkmcnt(7)
; #define RW_LD_UPD(buf, qb) do { _Pragma("unroll") for (int q_ = 0; q_ < UB; ++q_) { const int qq_ = UB * (qb) + q_; \
;                 wq[buf][q_] = *(const LAS f32x4*)(st + 4 * qq_); bq[buf][q_] = *(const LAS f32x4*)(st + 128 + 4 * qq_); kq[buf][q_] = *(const LAS f32x4*)(st + 192 + 4 * qq_); \
;                 if (MODE == 1) rq[buf][q_] = *(const LAS f32x4*)(st + 256 + 4 * qq_); } } while (0)
; template <int MODE> __device__ __forceinline__ void rwkv_item(const Params& P, int e, int c, int h, LAS float* slab, int lane) {
;     ...
;             f32x2 y0 = {0.f, 0.f}, y1 = {0.f, 0.f};
; #pragma unroll
;             for (int qb = 0; qb < NUB; ++qb) {
;                 if (NB == 2) { if (qb + 1 < NUB) RW_LD_UPD((qb + 1) & 1, qb + 1); } else RW_LD_UPD(0, qb);
;                 __builtin_amdgcn_sched_barrier(0);
; #pragma unroll
;                 for (int q = 0; q < UB; ++q) {
;                     const int qq = UB * qb + q;
;                     const f32x4 w4 = wq[qb & (NB - 1)][q], b4 = bq[qb & (NB - 1)][q], k4 = kq[qb & (NB - 1)][q];
;                     if (MODE == 0) {
;                         S2[2 * qq] = S2[2 * qq] * (f32x2){w4.x, w4.y} + (f32x2){b4.x, b4.y} * nsk;
;                         S2[2 * qq + 1] = S2[2 * qq + 1] * (f32x2){w4.z, w4.w} + (f32x2){b4.z, b4.w} * nsk;
;                         C2[2 * qq] = C2[2 * qq] * (f32x2){w4.x, w4.y} + (f32x2){b4.x, b4.y} * nskC + (f32x2){k4.x, k4.y} * v;
;                         C2[2 * qq + 1] = C2[2 * qq + 1] * (f32x2){w4.z, w4.w} + (f32x2){b4.z, b4.w} * nskC + (f32x2){k4.z, k4.w} * v;
;                     } else {
;                         S2[2 * qq] = S2[2 * qq] * (f32x2){w4.x, w4.y} + (f32x2){b4.x, b4.y} * nsk + (f32x2){k4.x, k4.y} * v;
;                         S2[2 * qq + 1] = S2[2 * qq + 1] * (f32x2){w4.z, w4.w} + (f32x2){b4.z, b4.w} * nsk + (f32x2){k4.z, k4.w} * v;
;                         const f32x4 r4 = rq[qb & (NB - 1)][q]; y0 += S2[2 * qq] * (f32x2){r4.x, r4.y}; y1 += S2[2 * qq + 1] * (f32x2){r4.z, r4.w};
;                     }
;                 }
;                 __builtin_amdgcn_sched_barrier(0);
;             }
	v_mfma_f32_4x4x1_16b_f32 v[112:115], v130, v208, v[112:115]
	v_mfma_f32_4x4x1_16b_f32 v[124:127], v130, v250, v[124:127]
	ds_read_b32 v130, v139 offset:816
	s_waitcnt lgkmcnt(7)
	v_mfma_f32_4x4x1_16b_f32 v[104:107], v131, v208, v[104:107]
	v_mfma_f32_4x4x1_16b_f32 v[120:123], v131, v250, v[120:123]
	ds_read_b32 v131, v139 offset:592
	s_waitcnt lgkmcnt(7)
	v_mfma_f32_4x4x1_16b_f32 v[124:127], v132, v152, v[124:127]
	ds_read_b32 v132, v139 offset:832
	s_waitcnt lgkmcnt(7)
	v_mfma_f32_4x4x1_16b_f32 v[92:95], v133, v208, v[92:95]
	v_mfma_f32_4x4x1_16b_f32 v[116:119], v133, v250, v[116:119]
	ds_read_b32 v133, v139 offset:608
	s_waitcnt lgkmcnt(7)
	v_mfma_f32_4x4x1_16b_f32 v[120:123], v134, v152, v[120:123]
	ds_read_b32 v134, v139 offset:848
	s_waitcnt lgkmcnt(7)
	v_mfma_f32_4x4x1_16b_f32 v[76:79], v135, v208, v[76:79]
	v_mfma_f32_4x4x1_16b_f32 v[108:111], v135, v250, v[108:111]
	ds_read_b32 v135, v139 offset:624
	s_waitcnt lgkmcnt(7)
	v_mfma_f32_4x4x1_16b_f32 v[116:119], v136, v152, v[116:119]
	ds_read_b32 v136, v139 offset:864
	s_waitcnt lgkmcnt(7)
	v_mfma_f32_4x4x1_16b_f32 v[64:67], v138, v208, v[64:67]
	v_mfma_f32_4x4x1_16b_f32 v[96:99], v138, v250, v[96:99]
	ds_read_b32 v138, v139 offset:640
	s_waitcnt lgkmcnt(7)
	v_mfma_f32_4x4x1_16b_f32 v[108:111], v130, v152, v[108:111]
	ds_read_b32 v130, v139 offset:880
	s_waitcnt lgkmcnt(7)
	v_mfma_f32_4x4x1_16b_f32 v[100:103], v131, v208, v[100:103]
	v_mfma_f32_4x4x1_16b_f32 v[80:83], v131, v250, v[80:83]
	ds_read_b32 v131, v139 offset:656
	s_waitcnt lgkmcnt(7)
	v_mfma_f32_4x4x1_16b_f32 v[96:99], v132, v152, v[96:99]
	ds_read_b32 v132, v139 offset:896
	s_waitcnt lgkmcnt(7)
	v_mfma_f32_4x4x1_16b_f32 v[88:91], v133, v208, v[88:91]
	v_mfma_f32_4x4x1_16b_f32 v[68:71], v133, v250, v[68:71]
	ds_read_b32 v133, v139 offset:672
	s_waitcnt lgkmcnt(7)
	v_mfma_f32_4x4x1_16b_f32 v[80:83], v134, v152, v[80:83]
	ds_read_b32 v134, v139 offset:912
	s_waitcnt lgkmcnt(7)
	v_mfma_f32_4x4x1_16b_f32 v[84:87], v135, v208, v[84:87]
	v_mfma_f32_4x4x1_16b_f32 v[52:55], v135, v250, v[52:55]
	ds_read_b32 v135, v139 offset:688
	s_waitcnt lgkmcnt(7)
	v_mfma_f32_4x4x1_16b_f32 v[68:71], v136, v152, v[68:71]
	ds_read_b32 v136, v139 offset:928
	s_waitcnt lgkmcnt(7)
	v_mfma_f32_4x4x1_16b_f32 v[72:75], v138, v208, v[72:75]
	v_mfma_f32_4x4x1_16b_f32 v[44:47], v138, v250, v[44:47]
	ds_read_b32 v138, v139 offset:704
	s_waitcnt lgkmcnt(7)
	v_mfma_f32_4x4x1_16b_f32 v[52:55], v130, v152, v[52:55]
	ds_read_b32 v130, v139 offset:944
	s_waitcnt lgkmcnt(7)
	v_mfma_f32_4x4x1_16b_f32 v[60:63], v131, v208, v[60:63]
	v_mfma_f32_4x4x1_16b_f32 v[32:35], v131, v250, v[32:35]
	ds_read_b32 v131, v139 offset:720
	s_waitcnt lgkmcnt(7)
	v_mfma_f32_4x4x1_16b_f32 v[44:47], v132, v152, v[44:47]
	ds_read_b32 v132, v139 offset:960
	s_waitcnt lgkmcnt(7)
	v_mfma_f32_4x4x1_16b_f32 v[56:59], v133, v208, v[56:59]
	v_mfma_f32_4x4x1_16b_f32 v[24:27], v133, v250, v[24:27]
	ds_read_b32 v133, v139 offset:736
	s_waitcnt lgkmcnt(7)
	v_mfma_f32_4x4x1_16b_f32 v[32:35], v134, v152, v[32:35]
	ds_read_b32 v134, v139 offset:976
	s_waitcnt lgkmcnt(7)
	v_mfma_f32_4x4x1_16b_f32 v[48:51], v135, v208, v[48:51]
	v_mfma_f32_4x4x1_16b_f32 v[16:19], v135, v250, v[16:19]
	ds_read_b32 v135, v139 offset:752
	s_waitcnt lgkmcnt(7)
	v_mfma_f32_4x4x1_16b_f32 v[24:27], v136, v152, v[24:27]
	ds_read_b32 v136, v139 offset:992
	s_waitcnt lgkmcnt(7)
	v_mfma_f32_4x4x1_16b_f32 v[40:43], v138, v208, v[40:43]
	v_mfma_f32_4x4x1_16b_f32 v[12:15], v138, v250, v[12:15]
	ds_read_b32 v138, v139 offset:1008
	s_waitcnt lgkmcnt(7)
	v_mfma_f32_4x4x1_16b_f32 v[16:19], v130, v152, v[16:19]
	s_waitcnt lgkmcnt(6)
	v_mfma_f32_4x4x1_16b_f32 v[36:39], v131, v208, v[36:39]
	v_mfma_f32_4x4x1_16b_f32 v[8:11], v131, v250, v[8:11]
	s_waitcnt lgkmcnt(5)
	v_mfma_f32_4x4x1_16b_f32 v[12:15], v132, v152, v[12:15]
	s_waitcnt lgkmcnt(4)
	v_mfma_f32_4x4x1_16b_f32 v[28:31], v133, v208, v[28:31]
	v_mfma_f32_4x4x1_16b_f32 v[4:7], v133, v250, v[4:7]
	s_waitcnt lgkmcnt(3)
	v_mfma_f32_4x4x1_16b_f32 v[8:11], v134, v152, v[8:11]
	s_waitcnt lgkmcnt(2)
	v_mfma_f32_4x4x1_16b_f32 v[20:23], v135, v208, v[20:23]
	v_mfma_f32_4x4x1_16b_f32 v[0:3], v135, v250, v[0:3]
	s_waitcnt lgkmcnt(1)
	v_mfma_f32_4x4x1_16b_f32 v[4:7], v136, v152, v[4:7]
	s_waitcnt lgkmcnt(0)
	s_nop 0
	v_mfma_f32_4x4x1_16b_f32 v[0:3], v138, v152, v[0:3]
	s_addk_i32 s2, 0x800
	s_cmpk_eq_i32 s2, 0x4000
	s_cbranch_scc0 .Lm0_step
	s_add_i32 s23, s23, 1
	s_cmp_eq_u32 s23, 8
	s_cbranch_scc0 .Lm0_sub
; template <int MODE> __device__ __forceinline__ void rwkv_item(const Params& P, int e, int c, int h, LAS float* slab, int lane) {
;     ...
;     if (MODE == 0) {
; #pragma unroll
;         for (int q = 0; q < 16; ++q) {
;             *(f32x4*)(MCM + rowoff + 4 * q) = (f32x4){S2[2 * q].x, S2[2 * q].y, S2[2 * q + 1].x, S2[2 * q + 1].y};
;             *(f32x4*)(MCC + rowoff + 4 * q) = (f32x4){C2[2 * q].x, C2[2 * q].y, C2[2 * q + 1].x, C2[2 * q + 1].y};
;         }
;     }
; template <int MODE> __device__ __forceinline__ void stage_rwkv_scan(const Params& P, int e, LAS unsigned char* lds) {
;     ...
;     for (int it = gw; it < RNCH * 8; it += ngw) rwkv_item<MODE>(P, e, it >> 3, it & 7, slab, lane);
	ds_write_b32 v129, v137
	v_mov_b32_e32 v233, s21
	s_waitcnt lgkmcnt(0)
	ds_read_b128 v[214:217], v233
	ds_read_b128 v[234:237], v233 offset:16
	ds_read_b128 v[238:241], v233 offset:32
	ds_read_b128 v[242:245], v233 offset:48
	s_waitcnt lgkmcnt(3)
	v_pk_mul_f32 v[112:113], v[112:113], v[214:215]
	v_pk_mul_f32 v[114:115], v[114:115], v[216:217]
	v_pk_mul_f32 v[124:125], v[124:125], v[214:215]
	v_pk_mul_f32 v[126:127], v[126:127], v[216:217]
	s_waitcnt lgkmcnt(2)
	v_pk_mul_f32 v[104:105], v[104:105], v[234:235]
	v_pk_mul_f32 v[106:107], v[106:107], v[236:237]
	v_pk_mul_f32 v[120:121], v[120:121], v[234:235]
	v_pk_mul_f32 v[122:123], v[122:123], v[236:237]
	s_waitcnt lgkmcnt(1)
	v_pk_mul_f32 v[92:93], v[92:93], v[238:239]
	v_pk_mul_f32 v[94:95], v[94:95], v[240:241]
	v_pk_mul_f32 v[116:117], v[116:117], v[238:239]
	v_pk_mul_f32 v[118:119], v[118:119], v[240:241]
	s_waitcnt lgkmcnt(0)
	v_pk_mul_f32 v[76:77], v[76:77], v[242:243]
	v_pk_mul_f32 v[78:79], v[78:79], v[244:245]
	v_pk_mul_f32 v[108:109], v[108:109], v[242:243]
	v_pk_mul_f32 v[110:111], v[110:111], v[244:245]
	ds_read_b128 v[214:217], v233 offset:64
	ds_read_b128 v[234:237], v233 offset:80
	ds_read_b128 v[238:241], v233 offset:96
	ds_read_b128 v[242:245], v233 offset:112
	s_waitcnt lgkmcnt(3)
	v_pk_mul_f32 v[64:65], v[64:65], v[214:215]
	v_pk_mul_f32 v[66:67], v[66:67], v[216:217]
	v_pk_mul_f32 v[96:97], v[96:97], v[214:215]
	v_pk_mul_f32 v[98:99], v[98:99], v[216:217]
	s_waitcnt lgkmcnt(2)
	v_pk_mul_f32 v[100:101], v[100:101], v[234:235]
	v_pk_mul_f32 v[102:103], v[102:103], v[236:237]
	v_pk_mul_f32 v[80:81], v[80:81], v[234:235]
	v_pk_mul_f32 v[82:83], v[82:83], v[236:237]
	s_waitcnt lgkmcnt(1)
	v_pk_mul_f32 v[88:89], v[88:89], v[238:239]
	v_pk_mul_f32 v[90:91], v[90:91], v[240:241]
	v_pk_mul_f32 v[68:69], v[68:69], v[238:239]
	v_pk_mul_f32 v[70:71], v[70:71], v[240:241]
	s_waitcnt lgkmcnt(0)
	v_pk_mul_f32 v[84:85], v[84:85], v[242:243]
	v_pk_mul_f32 v[86:87], v[86:87], v[244:245]
	v_pk_mul_f32 v[52:53], v[52:53], v[242:243]
	v_pk_mul_f32 v[54:55], v[54:55], v[244:245]
	ds_read_b128 v[214:217], v233 offset:128
	ds_read_b128 v[234:237], v233 offset:144
	ds_read_b128 v[238:241], v233 offset:160
	ds_read_b128 v[242:245], v233 offset:176
	s_waitcnt lgkmcnt(3)
	v_pk_mul_f32 v[72:73], v[72:73], v[214:215]
	v_pk_mul_f32 v[74:75], v[74:75], v[216:217]
	v_pk_mul_f32 v[44:45], v[44:45], v[214:215]
	v_pk_mul_f32 v[46:47], v[46:47], v[216:217]
	s_waitcnt lgkmcnt(2)
	v_pk_mul_f32 v[60:61], v[60:61], v[234:235]
	v_pk_mul_f32 v[62:63], v[62:63], v[236:237]
	v_pk_mul_f32 v[32:33], v[32:33], v[234:235]
	v_pk_mul_f32 v[34:35], v[34:35], v[236:237]
	s_waitcnt lgkmcnt(1)
	v_pk_mul_f32 v[56:57], v[56:57], v[238:239]
	v_pk_mul_f32 v[58:59], v[58:59], v[240:241]
	v_pk_mul_f32 v[24:25], v[24:25], v[238:239]
	v_pk_mul_f32 v[26:27], v[26:27], v[240:241]
	s_waitcnt lgkmcnt(0)
	v_pk_mul_f32 v[48:49], v[48:49], v[242:243]
	v_pk_mul_f32 v[50:51], v[50:51], v[244:245]
	v_pk_mul_f32 v[16:17], v[16:17], v[242:243]
	v_pk_mul_f32 v[18:19], v[18:19], v[244:245]
	ds_read_b128 v[214:217], v233 offset:192
	ds_read_b128 v[234:237], v233 offset:208
	ds_read_b128 v[238:241], v233 offset:224
	ds_read_b128 v[242:245], v233 offset:240
	s_waitcnt lgkmcnt(3)
	v_pk_mul_f32 v[40:41], v[40:41], v[214:215]
	v_pk_mul_f32 v[42:43], v[42:43], v[216:217]
	v_pk_mul_f32 v[12:13], v[12:13], v[214:215]
	v_pk_mul_f32 v[14:15], v[14:15], v[216:217]
	s_waitcnt lgkmcnt(2)
	v_pk_mul_f32 v[36:37], v[36:37], v[234:235]
	v_pk_mul_f32 v[38:39], v[38:39], v[236:237]
	v_pk_mul_f32 v[8:9], v[8:9], v[234:235]
	v_pk_mul_f32 v[10:11], v[10:11], v[236:237]
	s_waitcnt lgkmcnt(1)
	v_pk_mul_f32 v[28:29], v[28:29], v[238:239]
	v_pk_mul_f32 v[30:31], v[30:31], v[240:241]
	v_pk_mul_f32 v[4:5], v[4:5], v[238:239]
	v_pk_mul_f32 v[6:7], v[6:7], v[240:241]
	s_waitcnt lgkmcnt(0)
	v_pk_mul_f32 v[20:21], v[20:21], v[242:243]
	v_pk_mul_f32 v[22:23], v[22:23], v[244:245]
	v_pk_mul_f32 v[0:1], v[0:1], v[242:243]
	v_pk_mul_f32 v[2:3], v[2:3], v[244:245]
	s_lshl_b32 s2, s20, 6
	v_or_b32_e32 v204, s2, v128
	v_lshlrev_b32_e32 v204, 8, v204
	s_add_i32 s20, s20, s58
	global_store_dwordx4 v204, v[112:115], s[18:19]
	global_store_dwordx4 v204, v[124:127], s[8:9]
	global_store_dwordx4 v204, v[104:107], s[18:19] offset:16
	global_store_dwordx4 v204, v[120:123], s[8:9] offset:16
	global_store_dwordx4 v204, v[92:95], s[18:19] offset:32
	global_store_dwordx4 v204, v[116:119], s[8:9] offset:32
	global_store_dwordx4 v204, v[76:79], s[18:19] offset:48
	global_store_dwordx4 v204, v[108:111], s[8:9] offset:48
	global_store_dwordx4 v204, v[64:67], s[18:19] offset:64
	global_store_dwordx4 v204, v[96:99], s[8:9] offset:64
	global_store_dwordx4 v204, v[100:103], s[18:19] offset:80
	global_store_dwordx4 v204, v[80:83], s[8:9] offset:80
	global_store_dwordx4 v204, v[88:91], s[18:19] offset:96
	global_store_dwordx4 v204, v[68:71], s[8:9] offset:96
	global_store_dwordx4 v204, v[84:87], s[18:19] offset:112
	global_store_dwordx4 v204, v[52:55], s[8:9] offset:112
	global_store_dwordx4 v204, v[72:75], s[18:19] offset:128
	global_store_dwordx4 v204, v[44:47], s[8:9] offset:128
	global_store_dwordx4 v204, v[60:63], s[18:19] offset:144
	global_store_dwordx4 v204, v[32:35], s[8:9] offset:144
	global_store_dwordx4 v204, v[56:59], s[18:19] offset:160
	global_store_dwordx4 v204, v[24:27], s[8:9] offset:160
	global_store_dwordx4 v204, v[48:51], s[18:19] offset:176
	global_store_dwordx4 v204, v[16:19], s[8:9] offset:176
	global_store_dwordx4 v204, v[40:43], s[18:19] offset:192
	global_store_dwordx4 v204, v[12:15], s[8:9] offset:192
	global_store_dwordx4 v204, v[36:39], s[18:19] offset:208
	global_store_dwordx4 v204, v[8:11], s[8:9] offset:208
	global_store_dwordx4 v204, v[28:31], s[18:19] offset:224
	global_store_dwordx4 v204, v[4:7], s[8:9] offset:224
	global_store_dwordx4 v204, v[20:23], s[18:19] offset:240
	global_store_dwordx4 v204, v[0:3], s[8:9] offset:240
	s_cmpk_gt_i32 s20, 0x7ff
	s_cbranch_scc0 .LBB0_262
	v_mov_b32_e32 v210, 1
	v_mov_b64_e32 v[244:245], 0x180
	v_mov_b64_e32 v[246:247], 0x80
	v_mov_b64_e32 v[248:249], 0x7f
